# strategy 4: one static s_setprio 1 for waves 4-7 (SIMD partners of 0-3) during the attention phase
# baseline (speedup 1.0000x reference)
.LBB0_521:
	s_xor_b32 s10, s16, s14
	s_lshl_b32 s8, s10, 8
	s_lshl_b32 s7, s16, 9
	s_and_b32 s11, s8, 0x100
	s_or_b32 s62, s11, s7
	v_lshl_add_u64 v[134:135], v[122:123], 0, s[62:63]
	v_mad_u64_u32 v[2:3], s[8:9], v134, s59, v[124:125]
	v_mov_b32_e32 v0, v3
	v_mad_u64_u32 v[4:5], s[8:9], v135, s59, v[0:1]
	v_mov_b32_e32 v3, v4
	global_load_dwordx4 v[66:69], v[2:3], off
	global_load_dwordx4 v[70:73], v[2:3], off offset:32
	global_load_dwordx4 v[74:77], v[2:3], off offset:64
	global_load_dwordx4 v[78:81], v[2:3], off offset:96
	global_load_dwordx4 v[82:85], v[2:3], off offset:128
	global_load_dwordx4 v[86:89], v[2:3], off offset:160
	s_waitcnt lgkmcnt(0)
	s_barrier
	global_load_dwordx4 v[90:93], v[126:127], off
	global_load_dwordx4 v[94:97], v[126:127], off offset:128
	v_mov_b32_e32 v2, v1
	v_mov_b32_e32 v3, v1
	v_mov_b32_e32 v0, v1
	s_waitcnt vmcnt(16)
	v_mov_b64_e32 v[100:101], v[2:3]
	v_mov_b64_e32 v[98:99], v[0:1]
	global_load_dwordx4 v[98:101], v[128:129], off
	global_load_dwordx4 v[220:223], v[132:133], off
	global_load_dwordx4 v[224:227], v[132:133], off offset:128
	global_load_dwordx4 v[228:231], v[130:131], off
	s_mov_b64 s[24:25], 0x20000
	v_lshl_add_u64 v[136:137], v[132:133], 0, s[24:25]
	v_lshl_add_u64 v[138:139], v[130:131], 0, s[30:31]
	global_load_dwordx4 v[242:245], v[136:137], off
	global_load_dwordx4 v[246:249], v[136:137], off offset:128
	global_load_dwordx4 v[164:167], v[138:139], off
	v_lshl_add_u64 v[136:137], v[136:137], 0, s[24:25]
	v_lshl_add_u64 v[138:139], v[138:139], 0, s[30:31]
	v_add_u32_e32 v0, 0, v112
	s_waitcnt vmcnt(3)
	ds_write_b128 v0, v[90:93]
	v_add_u32_e32 v0, 0, v113
	s_nop 0
	ds_write_b128 v0, v[94:97] offset:13312
	s_and_saveexec_b64 s[8:9], s[0:1]
	v_add_u32_e32 v0, 0, v115
	ds_write_b128 v0, v[98:101] offset:128
	s_or_b64 exec, exec, s[8:9]
	ds_write_b128 v112, v[220:223] offset:22528
	ds_write_b128 v113, v[224:227] offset:35840
	ds_write_b128 v115, v[228:231] offset:22656
	global_load_dwordx4 v[90:93], v[136:137], off
	global_load_dwordx4 v[94:97], v[136:137], off offset:128
	global_load_dwordx4 v[98:101], v[138:139], off
	v_lshl_add_u64 v[136:137], v[136:137], 0, s[24:25]
	v_lshl_add_u64 v[138:139], v[138:139], 0, s[30:31]
	s_add_i32 s8, s15, s11
	s_lshr_b32 s8, s8, 6
	v_mov_b32_e32 v14, v1
	v_mov_b32_e32 v15, v1
	s_waitcnt lgkmcnt(0)
	s_barrier
	s_sub_i32 s18, 0, s8
	s_and_b32 s8, s10, 1
	v_mov_b32_e32 v0, v1
	v_mov_b32_e32 v2, v1
	v_mov_b32_e32 v3, v1
	v_mov_b32_e32 v4, v1
	v_mov_b32_e32 v5, v1
	v_mov_b32_e32 v6, v1
	v_mov_b32_e32 v7, v1
	v_mov_b32_e32 v8, v1
	v_mov_b32_e32 v9, v1
	v_mov_b32_e32 v10, v1
	v_mov_b32_e32 v11, v1
	v_mov_b32_e32 v12, v1
	v_mov_b32_e32 v13, v1
	v_mov_b64_e32 v[32:33], v[14:15]
	s_add_i32 s7, s62, 0x100
	s_lshl_b32 s8, s8, 8
	v_mov_b64_e32 v[30:31], v[12:13]
	v_mov_b64_e32 v[28:29], v[10:11]
	v_mov_b64_e32 v[26:27], v[8:9]
	v_mov_b64_e32 v[24:25], v[6:7]
	v_mov_b64_e32 v[22:23], v[4:5]
	v_mov_b64_e32 v[20:21], v[2:3]
	v_mov_b64_e32 v[18:19], v[0:1]
	v_mov_b64_e32 v[16:17], v[14:15]
	s_lshr_b32 s7, s7, 6
	s_mov_b32 s19, 1
	s_sub_i32 s20, 0, s8
	v_subrev_u32_e32 v121, s11, v114
	v_mov_b32_e32 v144, 0xf149f2ca
	v_mov_b32_e32 v143, 0
	s_nop 0
	s_nop 0
	s_mov_b32 s21, s17
	v_mov_b64_e32 v[14:15], v[12:13]
	v_mov_b64_e32 v[12:13], v[10:11]
	v_mov_b64_e32 v[10:11], v[8:9]
	v_mov_b64_e32 v[8:9], v[6:7]
	v_mov_b64_e32 v[6:7], v[4:5]
	v_mov_b64_e32 v[4:5], v[2:3]
	v_mov_b64_e32 v[2:3], v[0:1]
	v_mov_b32_e32 v203, 0xf149f2ca
	v_mov_b32_e32 v146, 0
	v_mov_b32_e32 v147, 0
	v_mov_b32_e32 v148, 0
	v_mov_b32_e32 v149, 0
	v_mov_b32_e32 v150, 0
	v_mov_b32_e32 v151, 0
	v_mov_b32_e32 v152, 0
	v_mov_b32_e32 v153, 0
	v_mov_b32_e32 v154, 0
	v_mov_b32_e32 v155, 0
	v_mov_b32_e32 v156, 0
	v_mov_b32_e32 v157, 0
	v_mov_b32_e32 v158, 0
	v_mov_b32_e32 v159, 0
	v_mov_b32_e32 v160, 0
	v_mov_b32_e32 v161, 0
	v_mov_b32_e32 v169, v142
	v_add_u32_e32 v250, 22528, v142
	v_add_u32_e32 v251, 45056, v142
	s_mov_b64 s[34:35], 0x20000
	s_add_i32 s36, s7, -4
	s_add_i32 s37, s7, -3
	v_readfirstlane_b32 s38, v109
	s_nop 3
	s_lshl_b32 s38, s38, 5
	s_or_b32 s38, s38, 31
	s_cmp_eq_u32 s36, 0
	s_cselect_b64 s[10:11], -1, 0
	s_cmpk_lt_u32 s93, 0x100
	s_cbranch_scc1 .Lat_prio_skip
	s_setprio 1
.Lat_prio_skip:
	s_branch .Lat_first
.Lat_head0:
	ds_read_b128 v[170:173], v140
	ds_read_b128 v[174:177], v140 offset:32
	ds_read_b128 v[178:181], v140 offset:64
	ds_read_b128 v[182:185], v140 offset:96
	ds_read_b128 v[186:189], v140 offset:128
	ds_read_b128 v[190:193], v140 offset:160
	ds_read_b128 v[204:207], v141
	ds_read_b128 v[208:211], v141 offset:32
	global_load_dwordx4 v[220:223], v[136:137], off
	global_load_dwordx4 v[224:227], v[136:137], off offset:128
	global_load_dwordx4 v[228:231], v[138:139], off
	s_waitcnt lgkmcnt(7)
	v_mfma_f32_32x32x16_bf16 v[50:65], v[170:173], v[66:69], v[146:161]
	ds_read_b128 v[170:173], v141 offset:64
	s_waitcnt lgkmcnt(7)
	v_mfma_f32_32x32x16_bf16 v[50:65], v[174:177], v[70:73], v[50:65]
	ds_read_b128 v[174:177], v141 offset:96
	s_waitcnt lgkmcnt(7)
	v_mfma_f32_32x32x16_bf16 v[50:65], v[178:181], v[74:77], v[50:65]
	ds_read_b128 v[178:181], v141 offset:128
	s_waitcnt lgkmcnt(7)
	v_mfma_f32_32x32x16_bf16 v[50:65], v[182:185], v[78:81], v[50:65]
	ds_read_b128 v[182:185], v141 offset:160
	s_waitcnt lgkmcnt(7)
	v_mfma_f32_32x32x16_bf16 v[50:65], v[186:189], v[82:85], v[50:65]
	s_waitcnt lgkmcnt(6)
	v_mfma_f32_32x32x16_bf16 v[50:65], v[190:193], v[86:89], v[50:65]
	ds_read_b64_tr_b16 v[186:187], v169 offset:13312
	ds_read_b64_tr_b16 v[188:189], v169 offset:14464
	ds_read_b64_tr_b16 v[190:191], v169 offset:13376
	ds_read_b64_tr_b16 v[192:193], v169 offset:14528
	s_waitcnt lgkmcnt(9)
	v_mfma_f32_32x32x16_bf16 v[34:49], v[204:207], v[66:69], v[146:161]
	ds_read_b64_tr_b16 v[204:205], v169 offset:15616
	ds_read_b64_tr_b16 v[206:207], v169 offset:16768
	s_waitcnt lgkmcnt(10)
	v_mfma_f32_32x32x16_bf16 v[34:49], v[208:211], v[70:73], v[34:49]
	ds_read_b64_tr_b16 v[208:209], v169 offset:15680
	ds_read_b64_tr_b16 v[210:211], v169 offset:16832
	s_nop 5
	v_exp_f32_e32 v50, v50
	v_exp_f32_e32 v51, v51
	v_exp_f32_e32 v52, v52
	v_exp_f32_e32 v53, v53
	s_waitcnt lgkmcnt(11)
	v_mfma_f32_32x32x16_bf16 v[34:49], v[170:173], v[74:77], v[34:49]
	v_exp_f32_e32 v54, v54
	v_exp_f32_e32 v55, v55
	v_exp_f32_e32 v56, v56
	v_exp_f32_e32 v57, v57
	v_cvt_pk_bf16_f32 v212, v50, v51
	v_cvt_pk_bf16_f32 v213, v52, v53
	v_cvt_pk_bf16_f32 v214, v54, v55
	v_cvt_pk_bf16_f32 v215, v56, v57
	s_waitcnt lgkmcnt(10)
	v_mfma_f32_32x32x16_bf16 v[34:49], v[174:177], v[78:81], v[34:49]
	v_add_f32_e32 v163, v50, v52
	v_add_f32_e32 v237, v51, v53
	s_waitcnt lgkmcnt(6)
	v_mfma_f32_32x32x16_bf16 v[18:33], v[186:189], v[212:215], v[18:33]
	v_exp_f32_e32 v58, v58
	v_exp_f32_e32 v59, v59
	v_exp_f32_e32 v60, v60
	s_waitcnt lgkmcnt(4)
	v_mfma_f32_32x32x16_bf16 v[2:17], v[190:193], v[212:215], v[2:17]
	v_exp_f32_e32 v61, v61
	v_exp_f32_e32 v62, v62
	v_exp_f32_e32 v63, v63
	v_mfma_f32_32x32x16_bf16 v[34:49], v[178:181], v[82:85], v[34:49]
	v_exp_f32_e32 v64, v64
	v_exp_f32_e32 v65, v65
	v_add_f32_e32 v163, v163, v54
	v_add_f32_e32 v237, v237, v55
	v_mfma_f32_32x32x16_bf16 v[34:49], v[182:185], v[86:89], v[34:49]
	v_cvt_pk_bf16_f32 v216, v58, v59
	v_cvt_pk_bf16_f32 v217, v60, v61
	v_cvt_pk_bf16_f32 v218, v62, v63
	v_cvt_pk_bf16_f32 v219, v64, v65
	v_add_f32_e32 v163, v163, v56
	v_add_f32_e32 v237, v237, v57
	v_add_f32_e32 v163, v163, v58
	v_add_f32_e32 v237, v237, v59
	s_waitcnt lgkmcnt(2)
	v_mfma_f32_32x32x16_bf16 v[18:33], v[204:207], v[216:219], v[18:33]
	v_add_f32_e32 v163, v163, v60
	v_add_f32_e32 v237, v237, v61
	v_add_f32_e32 v163, v163, v62
	s_waitcnt lgkmcnt(0)
	v_mfma_f32_32x32x16_bf16 v[2:17], v[208:211], v[216:219], v[2:17]
	v_add_f32_e32 v237, v237, v63
	v_add_f32_e32 v163, v163, v64
	v_add_f32_e32 v237, v237, v65
	s_barrier
	ds_read_b64_tr_b16 v[170:171], v169 offset:17920
	ds_read_b64_tr_b16 v[172:173], v169 offset:19072
	ds_read_b64_tr_b16 v[174:175], v169 offset:17984
	ds_read_b64_tr_b16 v[176:177], v169 offset:19136
	ds_read_b64_tr_b16 v[178:179], v169 offset:20224
	ds_read_b64_tr_b16 v[180:181], v169 offset:21376
	ds_read_b64_tr_b16 v[182:183], v169 offset:20288
	ds_read_b64_tr_b16 v[184:185], v169 offset:21440
	s_waitcnt vmcnt(6)
	ds_write_b128 v112, v[242:245] offset:45056
	ds_write_b128 v113, v[246:249] offset:58368
	ds_write_b128 v115, v[164:167] offset:45184
	v_exp_f32_e32 v34, v34
	v_exp_f32_e32 v35, v35
	v_exp_f32_e32 v36, v36
	v_exp_f32_e32 v37, v37
	v_exp_f32_e32 v38, v38
	v_exp_f32_e32 v39, v39
	v_exp_f32_e32 v40, v40
	v_exp_f32_e32 v41, v41
	v_cvt_pk_bf16_f32 v212, v34, v35
	v_cvt_pk_bf16_f32 v213, v36, v37
	v_cvt_pk_bf16_f32 v214, v38, v39
	v_cvt_pk_bf16_f32 v215, v40, v41
	v_exp_f32_e32 v42, v42
	v_exp_f32_e32 v43, v43
	s_waitcnt lgkmcnt(9)
	v_mfma_f32_32x32x16_bf16 v[18:33], v[170:173], v[212:215], v[18:33]
	s_waitcnt lgkmcnt(7)
	v_mfma_f32_32x32x16_bf16 v[2:17], v[174:177], v[212:215], v[2:17]
	v_exp_f32_e32 v44, v44
	v_add_f32_e32 v163, v163, v34
	v_exp_f32_e32 v45, v45
	v_add_f32_e32 v237, v237, v35
	v_exp_f32_e32 v46, v46
	v_add_f32_e32 v163, v163, v36
	v_exp_f32_e32 v47, v47
	v_add_f32_e32 v237, v237, v37
	v_exp_f32_e32 v48, v48
	v_add_f32_e32 v163, v163, v38
	v_exp_f32_e32 v49, v49
	v_add_f32_e32 v237, v237, v39
	v_add_f32_e32 v163, v163, v40
	v_add_f32_e32 v237, v237, v41
	v_cvt_pk_bf16_f32 v216, v42, v43
	v_cvt_pk_bf16_f32 v217, v44, v45
	v_cvt_pk_bf16_f32 v218, v46, v47
	v_cvt_pk_bf16_f32 v219, v48, v49
	v_add_f32_e32 v163, v163, v42
	v_add_f32_e32 v237, v237, v43
	s_waitcnt lgkmcnt(5)
	v_mfma_f32_32x32x16_bf16 v[18:33], v[178:181], v[216:219], v[18:33]
	s_waitcnt lgkmcnt(3)
	v_mfma_f32_32x32x16_bf16 v[2:17], v[182:185], v[216:219], v[2:17]
	v_add_f32_e32 v163, v163, v44
	v_add_f32_e32 v237, v237, v45
	v_add_f32_e32 v163, v163, v46
	v_add_f32_e32 v237, v237, v47
	v_add_f32_e32 v163, v163, v48
	v_add_f32_e32 v237, v237, v49
	v_add_f32_e32 v163, v163, v237
	v_cmp_lt_f32_e32 vcc, 0x45800000, v163
	v_add_f32_e32 v143, v143, v163
	s_cbranch_vccnz .Lat_postf0

.LBB0_541:
	s_mov_b64 s[2:3], s[94:95]
	v_mov_b32_e32 v0, v1
	s_setprio 0
	s_getreg_b32 s4, hwreg(HW_REG_XCC_ID, 0, 4)
	s_waitcnt vmcnt(0)
	s_nop 0
	v_mbcnt_lo_u32_b32 v0, -1, v0
	v_mbcnt_hi_u32_b32 v0, -1, v0
	v_sub_u32_e32 v0, 0, v0
	v_cmp_eq_u32_e32 vcc, s93, v0
	s_barrier
	s_and_saveexec_b64 s[0:1], vcc
	s_cbranch_execz .LBB0_593
	v_mov_b32_e32 v0, s90
	s_load_dwordx2 s[2:3], s[2:3], 0xc0
	s_waitcnt vmcnt(0) expcnt(0) lgkmcnt(0)
	ds_read_b32 v3, v0
	v_mov_b32_e32 v0, s57
	ds_read_b32 v2, v0
	s_and_b32 s33, s4, 15
	s_waitcnt lgkmcnt(1)
	v_cmp_ne_u32_e32 vcc, 0, v3
	s_cbranch_vccnz .LBB0_557
	s_add_u32 s4, s2, 0x3a600200
	s_addc_u32 s5, s3, 0
	s_add_u32 s6, s2, 0x3a600400
	s_addc_u32 s7, s3, 0
	s_add_u32 s8, s2, 0x3a600500
	s_addc_u32 s9, s3, 0
	s_add_u32 s10, s2, 0x3a600600
	s_addc_u32 s11, s3, 0
	s_add_u32 s12, s2, 0x3a600700
	s_addc_u32 s13, s3, 0
	s_add_u32 s14, s2, 0x3a600800
	s_addc_u32 s15, s3, 0
	s_add_u32 s16, s2, 0x3a600900
	s_addc_u32 s17, s3, 0
	s_add_u32 s18, s2, 0x3a600a00
	s_addc_u32 s19, s3, 0
	s_add_u32 s20, s2, 0x3a600b00
	s_addc_u32 s21, s3, 0
	s_add_u32 s22, s2, 0x3a600c00
	s_addc_u32 s23, s3, 0
	s_add_u32 s24, s2, 0x3a600d00
	s_addc_u32 s25, s3, 0
	s_add_u32 s26, s2, 0x3a600e00
	s_addc_u32 s27, s3, 0
	s_add_u32 s28, s2, 0x3a600f00
	s_addc_u32 s29, s3, 0
	s_add_u32 s34, s2, 0x3a601000
	s_addc_u32 s35, s3, 0
	s_add_u32 s36, s2, 0x3a601100
	s_addc_u32 s37, s3, 0
	s_add_u32 s38, s2, 0x3a601200
	s_addc_u32 s39, s3, 0
	s_add_u32 s40, s2, 0x3a601300
	s_addc_u32 s41, s3, 0
	s_mov_b32 s48, 1
	s_branch .LBB0_545
